# four P8 edits + P6 epilogue block-mean column sums: the 16-lane shfl_xor butterfly via ds_bpermute (LDS round trip per step) replaced by DPP adds (quad_perm / row_half_mirror / row_mirror), bit-identi
# speedup vs baseline: 1.0012x; 1.0012x over previous
;     __device__ __forceinline__ void operator()(f32x4 (&acc)[2][2][4][2], const Unit& u, const Order& S, int wr, int wc, int fr_, int fq_, LAS unsigned char*, int) const {
;     ...
; #pragma unroll
;             for (int bj = 0; bj < 2; ++bj)
; #pragma unroll
;                 for (int n = 0; n < 2; ++n)
; #pragma unroll
;                     for (int e = 0; e < 4; ++e) {
;                         float s = ks[bj][n][e];
;                         s += __shfl_xor(s, 1); s += __shfl_xor(s, 2); s += __shfl_xor(s, 4); s += __shfl_xor(s, 8);
;                         if (fr == 0) atomicAdd(dst + 32 * bj + 8 * fq + 4 * n + e, s);
;                     }
.LBB0_780:
	s_or_b64 exec, exec, s[2:3]
	s_nop 1
	v_add_f32_dpp v10, v11, v11 quad_perm:[1,0,3,2] row_mask:0xf bank_mask:0xf
	ds_bpermute_b32 v11, v13, v10
	s_waitcnt lgkmcnt(0)
	v_add_f32_e32 v24, v10, v11
	ds_bpermute_b32 v25, v16, v24
	v_pk_add_f32 v[10:11], v[148:149], 0 op_sel_hi:[1,0]
	s_waitcnt lgkmcnt(0)
	v_add_f32_e32 v24, v24, v25
	v_pk_add_f32 v[10:11], v[10:11], v[138:139]
	ds_bpermute_b32 v25, v17, v24
	v_pk_add_f32 v[10:11], v[10:11], v[126:127]
	s_nop 0
	v_pk_add_f32 v[10:11], v[10:11], v[110:111]
	s_nop 0
	v_pk_add_f32 v[10:11], v[10:11], v[94:95]
	s_nop 0
	v_pk_add_f32 v[10:11], v[10:11], v[78:79]
	s_nop 0
	v_pk_add_f32 v[10:11], v[10:11], v[62:63]
	s_nop 0
	v_pk_add_f32 v[10:11], v[10:11], v[38:39]
	s_and_saveexec_b64 s[2:3], vcc
	s_cbranch_execz .LBB0_782
	s_waitcnt lgkmcnt(0)
	v_add_f32_e32 v24, v24, v25
	global_atomic_add_f32 v[6:7], v24, off offset:4
.LBB0_782:
	s_or_b64 exec, exec, s[2:3]
	s_nop 1
	v_add_f32_dpp v10, v10, v10 quad_perm:[1,0,3,2] row_mask:0xf bank_mask:0xf
	s_nop 1
	v_add_f32_dpp v10, v10, v10 quad_perm:[2,3,0,1] row_mask:0xf bank_mask:0xf
	s_nop 1
	v_add_f32_dpp v10, v10, v10 row_half_mirror row_mask:0xf bank_mask:0xf
	s_nop 1
	v_add_f32_dpp v10, v10, v10 row_mirror row_mask:0xf bank_mask:0xf
	s_and_saveexec_b64 s[2:3], vcc
	s_cbranch_execz .LBB0_784
	s_waitcnt lgkmcnt(0)
	global_atomic_add_f32 v[6:7], v10, off offset:8
.LBB0_784:
	s_or_b64 exec, exec, s[2:3]
	s_nop 1
	v_add_f32_dpp v10, v11, v11 quad_perm:[1,0,3,2] row_mask:0xf bank_mask:0xf
	s_nop 1
	v_add_f32_dpp v10, v10, v10 quad_perm:[2,3,0,1] row_mask:0xf bank_mask:0xf
	s_nop 1
	v_add_f32_dpp v10, v10, v10 row_half_mirror row_mask:0xf bank_mask:0xf
	ds_bpermute_b32 v11, v17, v10
	s_and_saveexec_b64 s[2:3], vcc
	s_cbranch_execz .LBB0_786
	s_waitcnt lgkmcnt(0)
	v_add_f32_e32 v10, v10, v11
	global_atomic_add_f32 v[6:7], v10, off offset:12
.LBB0_786:
	s_or_b64 exec, exec, s[2:3]
	s_waitcnt lgkmcnt(0)
	v_pk_add_f32 v[10:11], v[146:147], 0 op_sel_hi:[1,0]
	s_nop 0
	v_pk_add_f32 v[10:11], v[10:11], v[136:137]
	s_nop 0
	v_pk_add_f32 v[10:11], v[10:11], v[124:125]
	s_nop 0
	v_pk_add_f32 v[10:11], v[10:11], v[108:109]
	s_nop 0
	v_pk_add_f32 v[10:11], v[10:11], v[92:93]
	s_nop 0
	v_pk_add_f32 v[10:11], v[10:11], v[76:77]
	s_nop 0
	v_pk_add_f32 v[10:11], v[10:11], v[60:61]
	s_nop 0
	v_pk_add_f32 v[10:11], v[10:11], v[36:37]
	s_nop 1
	v_add_f32_dpp v10, v10, v10 quad_perm:[1,0,3,2] row_mask:0xf bank_mask:0xf
	s_nop 1
	v_add_f32_dpp v10, v10, v10 quad_perm:[2,3,0,1] row_mask:0xf bank_mask:0xf
	s_nop 1
	v_add_f32_dpp v10, v10, v10 row_half_mirror row_mask:0xf bank_mask:0xf
	s_nop 1
	v_add_f32_dpp v10, v10, v10 row_mirror row_mask:0xf bank_mask:0xf
	s_and_saveexec_b64 s[2:3], vcc
	s_cbranch_execz .LBB0_788
	s_waitcnt lgkmcnt(0)
	global_atomic_add_f32 v[6:7], v10, off offset:16
.LBB0_788:
	s_or_b64 exec, exec, s[2:3]
	s_nop 1
	v_add_f32_dpp v10, v11, v11 quad_perm:[1,0,3,2] row_mask:0xf bank_mask:0xf
	ds_bpermute_b32 v11, v13, v10
	s_waitcnt lgkmcnt(0)
	v_add_f32_e32 v24, v10, v11
	ds_bpermute_b32 v25, v16, v24
	v_pk_add_f32 v[10:11], v[32:33], 0 op_sel_hi:[1,0]
	s_waitcnt lgkmcnt(0)
	v_add_f32_e32 v24, v24, v25
	v_pk_add_f32 v[10:11], v[10:11], v[134:135]
	ds_bpermute_b32 v25, v17, v24
	v_pk_add_f32 v[10:11], v[10:11], v[122:123]
	s_nop 0
	v_pk_add_f32 v[10:11], v[10:11], v[106:107]
	s_nop 0
	v_pk_add_f32 v[10:11], v[10:11], v[90:91]
	s_nop 0
	v_pk_add_f32 v[10:11], v[10:11], v[74:75]
	s_nop 0
	v_pk_add_f32 v[10:11], v[10:11], v[58:59]
	s_nop 0
	v_pk_add_f32 v[10:11], v[10:11], v[34:35]
	s_and_saveexec_b64 s[2:3], vcc
	s_cbranch_execz .LBB0_790
	s_waitcnt lgkmcnt(0)
	v_add_f32_e32 v24, v24, v25
	global_atomic_add_f32 v[6:7], v24, off offset:20
.LBB0_790:
	s_or_b64 exec, exec, s[2:3]
	s_nop 1
	v_add_f32_dpp v10, v10, v10 quad_perm:[1,0,3,2] row_mask:0xf bank_mask:0xf
	s_nop 1
	v_add_f32_dpp v10, v10, v10 quad_perm:[2,3,0,1] row_mask:0xf bank_mask:0xf
	s_nop 1
	v_add_f32_dpp v10, v10, v10 row_half_mirror row_mask:0xf bank_mask:0xf
	s_nop 1
	v_add_f32_dpp v10, v10, v10 row_mirror row_mask:0xf bank_mask:0xf
	s_and_saveexec_b64 s[2:3], vcc
	s_cbranch_execz .LBB0_792
	s_waitcnt lgkmcnt(0)
	global_atomic_add_f32 v[6:7], v10, off offset:24
.LBB0_792:
	s_or_b64 exec, exec, s[2:3]
	s_nop 1
	v_add_f32_dpp v10, v11, v11 quad_perm:[1,0,3,2] row_mask:0xf bank_mask:0xf
	s_nop 1
	v_add_f32_dpp v10, v10, v10 quad_perm:[2,3,0,1] row_mask:0xf bank_mask:0xf
	s_nop 1
	v_add_f32_dpp v10, v10, v10 row_half_mirror row_mask:0xf bank_mask:0xf
	ds_bpermute_b32 v11, v17, v10
	s_and_saveexec_b64 s[2:3], vcc
	s_cbranch_execz .LBB0_794
	s_waitcnt lgkmcnt(0)
	v_add_f32_e32 v10, v10, v11
	global_atomic_add_f32 v[6:7], v10, off offset:28
;     __device__ __forceinline__ void operator()(f32x4 (&acc)[2][2][4][2], const Unit& u, const Order& S, int wr, int wc, int fr_, int fq_, LAS unsigned char*, int) const {
;     ...
; #pragma unroll
;             for (int bj = 0; bj < 2; ++bj)
; #pragma unroll
;                 for (int n = 0; n < 2; ++n)
; #pragma unroll
;                     for (int e = 0; e < 4; ++e) {
;                         float s = ks[bj][n][e];
;                         s += __shfl_xor(s, 1); s += __shfl_xor(s, 2); s += __shfl_xor(s, 4); s += __shfl_xor(s, 8);
;                         if (fr == 0) atomicAdd(dst + 32 * bj + 8 * fq + 4 * n + e, s);
;                     }
.LBB0_794:
	s_or_b64 exec, exec, s[2:3]
	s_waitcnt lgkmcnt(0)
	v_pk_add_f32 v[10:11], v[28:29], 0 op_sel_hi:[1,0]
	s_nop 0
	v_pk_add_f32 v[10:11], v[10:11], v[132:133]
	s_nop 0
	v_pk_add_f32 v[10:11], v[10:11], v[120:121]
	s_nop 0
	v_pk_add_f32 v[10:11], v[10:11], v[104:105]
	s_nop 0
	v_pk_add_f32 v[10:11], v[10:11], v[88:89]
	s_nop 0
	v_pk_add_f32 v[10:11], v[10:11], v[72:73]
	s_nop 0
	v_pk_add_f32 v[10:11], v[10:11], v[56:57]
	s_nop 0
	v_pk_add_f32 v[10:11], v[10:11], v[14:15]
	s_nop 1
	v_add_f32_dpp v10, v10, v10 quad_perm:[1,0,3,2] row_mask:0xf bank_mask:0xf
	s_nop 1
	v_add_f32_dpp v10, v10, v10 quad_perm:[2,3,0,1] row_mask:0xf bank_mask:0xf
	s_nop 1
	v_add_f32_dpp v10, v10, v10 row_half_mirror row_mask:0xf bank_mask:0xf
	s_nop 1
	v_add_f32_dpp v10, v10, v10 row_mirror row_mask:0xf bank_mask:0xf
	s_and_saveexec_b64 s[2:3], vcc
	s_cbranch_execz .LBB0_796
	s_waitcnt lgkmcnt(0)
	global_atomic_add_f32 v[6:7], v10, off offset:128
.LBB0_796:
	s_or_b64 exec, exec, s[2:3]
	s_nop 1
	v_add_f32_dpp v10, v11, v11 quad_perm:[1,0,3,2] row_mask:0xf bank_mask:0xf
	ds_bpermute_b32 v11, v13, v10
	s_waitcnt lgkmcnt(0)
	v_add_f32_e32 v24, v10, v11
	ds_bpermute_b32 v25, v16, v24
	v_pk_add_f32 v[10:11], v[22:23], 0 op_sel_hi:[1,0]
	s_nop 0
	v_pk_add_f32 v[10:11], v[10:11], v[130:131]
	s_nop 0
	v_pk_add_f32 v[10:11], v[10:11], v[118:119]
	s_nop 0
	v_pk_add_f32 v[14:15], v[10:11], v[102:103]
	s_waitcnt lgkmcnt(0)
	v_add_f32_e32 v10, v24, v25
	ds_bpermute_b32 v11, v17, v10
	v_pk_add_f32 v[14:15], v[14:15], v[86:87]
	s_nop 0
	v_pk_add_f32 v[14:15], v[14:15], v[70:71]
	s_nop 0
	v_pk_add_f32 v[14:15], v[14:15], v[54:55]
	s_nop 0
	v_pk_add_f32 v[8:9], v[14:15], v[8:9]
	s_and_saveexec_b64 s[2:3], vcc
	s_cbranch_execz .LBB0_798
	s_waitcnt lgkmcnt(0)
	v_add_f32_e32 v10, v10, v11
	global_atomic_add_f32 v[6:7], v10, off offset:132
.LBB0_798:
	s_or_b64 exec, exec, s[2:3]
	s_nop 1
	v_add_f32_dpp v8, v8, v8 quad_perm:[1,0,3,2] row_mask:0xf bank_mask:0xf
	s_nop 1
	v_add_f32_dpp v8, v8, v8 quad_perm:[2,3,0,1] row_mask:0xf bank_mask:0xf
	s_nop 1
	v_add_f32_dpp v8, v8, v8 row_half_mirror row_mask:0xf bank_mask:0xf
	s_nop 1
	v_add_f32_dpp v8, v8, v8 row_mirror row_mask:0xf bank_mask:0xf
	s_and_saveexec_b64 s[2:3], vcc
	s_cbranch_execz .LBB0_800
	s_waitcnt lgkmcnt(0)
	global_atomic_add_f32 v[6:7], v8, off offset:136
.LBB0_800:
	s_or_b64 exec, exec, s[2:3]
	s_nop 1
	v_add_f32_dpp v8, v9, v9 quad_perm:[1,0,3,2] row_mask:0xf bank_mask:0xf
	s_nop 1
	v_add_f32_dpp v8, v8, v8 quad_perm:[2,3,0,1] row_mask:0xf bank_mask:0xf
	s_nop 1
	v_add_f32_dpp v8, v8, v8 row_half_mirror row_mask:0xf bank_mask:0xf
	ds_bpermute_b32 v9, v17, v8
	s_and_saveexec_b64 s[2:3], vcc
	s_cbranch_execz .LBB0_802
	s_waitcnt lgkmcnt(0)
	v_add_f32_e32 v8, v8, v9
	global_atomic_add_f32 v[6:7], v8, off offset:140
.LBB0_802:
	s_or_b64 exec, exec, s[2:3]
	s_waitcnt lgkmcnt(0)
	v_pk_add_f32 v[8:9], v[20:21], 0 op_sel_hi:[1,0]
	s_nop 0
	v_pk_add_f32 v[8:9], v[8:9], v[30:31]
	s_nop 0
	v_pk_add_f32 v[8:9], v[8:9], v[116:117]
	s_nop 0
	v_pk_add_f32 v[8:9], v[8:9], v[100:101]
	s_nop 0
	v_pk_add_f32 v[8:9], v[8:9], v[84:85]
	s_nop 0
	v_pk_add_f32 v[8:9], v[8:9], v[68:69]
	s_nop 0
	v_pk_add_f32 v[8:9], v[8:9], v[52:53]
	s_nop 0
	v_pk_add_f32 v[4:5], v[8:9], v[4:5]
	s_nop 1
	v_add_f32_dpp v4, v4, v4 quad_perm:[1,0,3,2] row_mask:0xf bank_mask:0xf
	s_nop 1
	v_add_f32_dpp v4, v4, v4 quad_perm:[2,3,0,1] row_mask:0xf bank_mask:0xf
	s_nop 1
	v_add_f32_dpp v4, v4, v4 row_half_mirror row_mask:0xf bank_mask:0xf
	s_nop 1
	v_add_f32_dpp v4, v4, v4 row_mirror row_mask:0xf bank_mask:0xf
	s_and_saveexec_b64 s[2:3], vcc
	s_cbranch_execz .LBB0_804
	s_waitcnt lgkmcnt(0)
	global_atomic_add_f32 v[6:7], v4, off offset:144
.LBB0_804:
	s_or_b64 exec, exec, s[2:3]
	s_nop 1
	v_add_f32_dpp v4, v5, v5 quad_perm:[1,0,3,2] row_mask:0xf bank_mask:0xf
	ds_bpermute_b32 v5, v13, v4
	s_waitcnt lgkmcnt(0)
	v_add_f32_e32 v10, v4, v5
	ds_bpermute_b32 v11, v16, v10
	v_pk_add_f32 v[4:5], v[18:19], 0 op_sel_hi:[1,0]
	s_nop 0
	v_pk_add_f32 v[4:5], v[4:5], v[26:27]
	s_nop 0
	v_pk_add_f32 v[4:5], v[4:5], v[114:115]
	s_nop 0
	v_pk_add_f32 v[8:9], v[4:5], v[98:99]
	s_waitcnt lgkmcnt(0)
	v_add_f32_e32 v4, v10, v11
	ds_bpermute_b32 v5, v17, v4
	v_pk_add_f32 v[8:9], v[8:9], v[82:83]
	s_nop 0
	v_pk_add_f32 v[8:9], v[8:9], v[66:67]
	s_nop 0
	v_pk_add_f32 v[8:9], v[8:9], v[50:51]
	s_nop 0
	v_pk_add_f32 v[2:3], v[8:9], v[2:3]
	s_and_saveexec_b64 s[2:3], vcc
	s_cbranch_execz .LBB0_806
	s_waitcnt lgkmcnt(0)
	v_add_f32_e32 v4, v4, v5
	global_atomic_add_f32 v[6:7], v4, off offset:148
.LBB0_806:
	s_or_b64 exec, exec, s[2:3]
	s_nop 1
	v_add_f32_dpp v2, v2, v2 quad_perm:[1,0,3,2] row_mask:0xf bank_mask:0xf
	s_nop 1
	v_add_f32_dpp v2, v2, v2 quad_perm:[2,3,0,1] row_mask:0xf bank_mask:0xf
	s_nop 1
	v_add_f32_dpp v2, v2, v2 row_half_mirror row_mask:0xf bank_mask:0xf
	s_nop 1
	v_add_f32_dpp v2, v2, v2 row_mirror row_mask:0xf bank_mask:0xf
	s_and_saveexec_b64 s[2:3], vcc
	s_cbranch_execz .LBB0_808
	s_waitcnt lgkmcnt(0)
	global_atomic_add_f32 v[6:7], v2, off offset:152
.LBB0_808:
	s_or_b64 exec, exec, s[2:3]
	s_nop 1
	v_add_f32_dpp v2, v3, v3 quad_perm:[1,0,3,2] row_mask:0xf bank_mask:0xf
	s_nop 1
	v_add_f32_dpp v2, v2, v2 quad_perm:[2,3,0,1] row_mask:0xf bank_mask:0xf
	s_nop 1
	v_add_f32_dpp v2, v2, v2 row_half_mirror row_mask:0xf bank_mask:0xf
	ds_bpermute_b32 v3, v17, v2
	s_and_saveexec_b64 s[2:3], vcc
	s_cbranch_execz .LBB0_810
	s_waitcnt lgkmcnt(0)
	v_add_f32_e32 v2, v2, v3
	global_atomic_add_f32 v[6:7], v2, off offset:156
